# P6 gate-merge epilogue: touch the 16 gate pieces and 16 dst pieces up front (L2 prefetch) so per-group loads hit L2
# baseline (speedup 1.0000x reference)
; __device__ __forceinline__ float sigm(float x) { return 1.f / (1.f + __expf(-x)); }
;     __device__ __forceinline__ void operator()(const pg8::f32x4 (&acc)[2][2][4][2], const pg8::Unit& u, int wr, int wc, int fr, int fq) const {
;     ...
;         const int rowb = u.pm * 256 + wr * 64 + fr;
;     ...
; #pragma unroll
;             for (int ai = 0; ai < 2; ++ai)
; #pragma unroll
;                 for (int m = 0; m < 4; ++m) {
;                     const int row = rowb + ai * 128 + m * 16;
;                     const float rsv = rs8[ai][m];
;                     float sacc = 0.f;
; #pragma unroll
;                     for (int bj = 0; bj < 2; ++bj) {
;                         float o[8];
; #pragma unroll
;                         for (int n = 0; n < 2; ++n)
; #pragma unroll
;                             for (int j = 0; j < 4; ++j) o[4 * n + j] = acc[ai][bj][m][n][j] * rsv;
;                         if (sig) {
; #pragma unroll
;                             for (int e = 0; e < 8; ++e) o[e] = sigm(o[e]);
;                             if (mode == EM_Z2) { const f32x4 h0 = *(const f32x4*)(gain0 + colb - 2048 + bj * 128 + cl), h1_ = *(const f32x4*)(gain0 + colb - 2048 + bj * 128 + cl + 4);
; #pragma unroll
;                                 for (int e = 0; e < 4; ++e) { o[e] *= h0[e]; o[4 + e] *= h1_[e]; } }
;                         }
;                         if (gt) { float gv[8]; unpack8(*(const u32x4*)(gt + (size_t)row * Z2_LD + gcol + bj * 128 + cl), gv);
; #pragma unroll
;                             for (int e = 0; e < 8; ++e) o[e] *= gv[e]; }
;                         bf16_t* p = dst + (size_t)row * ldc + colb + bj * 128 + cl;
;                         if (addt) { float tv[8]; unpack8(*(const u32x4*)p, tv);
; #pragma unroll
;                             for (int e = 0; e < 8; ++e) o[e] += tv[e]; }
.LBB0_331:
	s_lshl_b32 s93, s59, 8
	v_add_u32_e32 v178, s93, v155
	v_cndmask_b32_e64 v0, 0, 1, s[52:53]
	v_mov_b32_e32 v134, 0
	v_cmp_ne_u32_e64 s[44:45], 1, v0
	s_andn2_b64 vcc, exec, s[52:53]
	v_ashrrev_i32_e32 v179, 31, v178
	s_cmp_eq_u64 s[72:73], 0
	s_cbranch_scc1 .Lgp_skip
	v_add_u32_e32 v140, s46, v156
	v_lshlrev_b32_e32 v140, 1, v140
	v_mov_b32_e32 v141, 0
	v_lshlrev_b64 v[142:143], 13, v[178:179]
	v_lshl_add_u64 v[140:141], v[140:141], 0, s[72:73]
	v_lshl_add_u64 v[140:141], v[140:141], 0, v[142:143]
	v_mov_b32_e32 v142, 0x20000
	v_mov_b32_e32 v143, 0
	global_load_dword v144, v[140:141], off
	global_load_dword v144, v[140:141], off offset:256
	v_lshl_add_u64 v[140:141], v[140:141], 0, v[142:143]
	global_load_dword v144, v[140:141], off
	global_load_dword v144, v[140:141], off offset:256
	v_lshl_add_u64 v[140:141], v[140:141], 0, v[142:143]
	global_load_dword v144, v[140:141], off
	global_load_dword v144, v[140:141], off offset:256
	v_lshl_add_u64 v[140:141], v[140:141], 0, v[142:143]
	global_load_dword v144, v[140:141], off
	global_load_dword v144, v[140:141], off offset:256
	v_lshl_add_u64 v[140:141], v[142:143], 2, v[140:141]
	v_lshl_add_u64 v[140:141], v[140:141], 0, v[142:143]
	global_load_dword v144, v[140:141], off
	global_load_dword v144, v[140:141], off offset:256
	v_lshl_add_u64 v[140:141], v[140:141], 0, v[142:143]
	global_load_dword v144, v[140:141], off
	global_load_dword v144, v[140:141], off offset:256
	v_lshl_add_u64 v[140:141], v[140:141], 0, v[142:143]
	global_load_dword v144, v[140:141], off
	global_load_dword v144, v[140:141], off offset:256
	v_lshl_add_u64 v[140:141], v[140:141], 0, v[142:143]
	global_load_dword v144, v[140:141], off
	global_load_dword v144, v[140:141], off offset:256
	s_cmp_eq_u64 s[48:49], 0
	s_cbranch_scc1 .Lgp_skip
	v_add_u32_e32 v140, s58, v156
	v_lshlrev_b32_e32 v140, 1, v140
	v_mov_b32_e32 v141, 0
	v_lshlrev_b64 v[142:143], 12, v[178:179]
	v_lshl_add_u64 v[140:141], v[140:141], 0, s[14:15]
	v_lshl_add_u64 v[140:141], v[140:141], 0, v[142:143]
	v_mov_b32_e32 v142, 0x10000
	v_mov_b32_e32 v143, 0
	global_load_dword v144, v[140:141], off
	global_load_dword v144, v[140:141], off offset:256
	v_lshl_add_u64 v[140:141], v[140:141], 0, v[142:143]
	global_load_dword v144, v[140:141], off
	global_load_dword v144, v[140:141], off offset:256
	v_lshl_add_u64 v[140:141], v[140:141], 0, v[142:143]
	global_load_dword v144, v[140:141], off
	global_load_dword v144, v[140:141], off offset:256
	v_lshl_add_u64 v[140:141], v[140:141], 0, v[142:143]
	global_load_dword v144, v[140:141], off
	global_load_dword v144, v[140:141], off offset:256
	v_lshl_add_u64 v[140:141], v[142:143], 2, v[140:141]
	v_lshl_add_u64 v[140:141], v[140:141], 0, v[142:143]
	global_load_dword v144, v[140:141], off
	global_load_dword v144, v[140:141], off offset:256
	v_lshl_add_u64 v[140:141], v[140:141], 0, v[142:143]
	global_load_dword v144, v[140:141], off
	global_load_dword v144, v[140:141], off offset:256
	v_lshl_add_u64 v[140:141], v[140:141], 0, v[142:143]
	global_load_dword v144, v[140:141], off
	global_load_dword v144, v[140:141], off offset:256
	v_lshl_add_u64 v[140:141], v[140:141], 0, v[142:143]
	global_load_dword v144, v[140:141], off
	global_load_dword v144, v[140:141], off offset:256
.Lgp_skip:
	v_mov_b32_e32 v136, 0
	s_cbranch_vccz .LBB0_343
	s_and_b64 vcc, exec, s[44:45]
	s_cbranch_vccz .LBB0_344

; #define PG8_BAR __builtin_amdgcn_s_barrier()
; template <class Epi, class Sched, bool ALIGN_EPI = false, bool SP2 = false>
; __device__ __forceinline__ void gemm_phase(PG8_LAS unsigned char* lds, int tid_in, const Gemm g, const Sched& S, const Epi& E) {
;     ...
;         cur = nxt; cA = nA; cB = nB; ++ui;
;         if constexpr (ALIGN_EPI) { if (wr == 1) PG8_BAR; }
;     }
.LBB0_620:
	s_andn2_b64 vcc, exec, s[56:57]
	s_cbranch_vccnz .LBB0_269
	s_barrier
	s_branch .LBB0_269
	s_nop 0
	s_nop 0
	s_nop 0
	s_nop 0
	s_nop 0
	s_nop 0
	s_nop 0
	s_nop 0
	s_nop 0
	s_nop 0
	s_nop 0
	s_nop 0
	s_nop 0
	s_nop 0
	s_nop 0
	s_nop 0
	s_nop 0
	s_nop 0
	s_nop 0
	s_nop 0
	s_nop 0
	s_nop 0
	s_nop 0
	s_nop 0
	s_nop 0
	s_nop 0
	s_nop 0
	s_nop 0
	s_nop 0
	s_nop 0
	s_nop 0
	s_nop 0
	s_nop 0
	s_nop 0
	s_nop 0
	s_nop 0
	s_nop 0
	s_nop 0
	s_nop 0
	s_nop 0
	s_nop 0
	s_nop 0
	s_nop 0
	s_nop 0
	s_nop 0
	s_nop 0
	s_nop 0
	s_nop 0
	s_nop 0
	s_nop 0
	s_nop 0
	s_nop 0
	s_nop 0
	s_nop 0
	s_nop 0
	s_nop 0
	s_nop 0
	s_nop 0
	s_nop 0
	s_nop 0
	s_nop 0
	s_nop 0
	s_nop 0
	s_nop 0
	s_nop 0
	s_nop 0
	s_nop 0
	s_nop 0
	s_nop 0
	s_nop 0
	s_nop 0
	s_nop 0
	s_nop 0
	s_nop 0
	s_nop 0
	s_nop 0
	s_nop 0
	s_nop 0
	s_nop 0
	s_nop 0
	s_nop 0
	s_nop 0
	s_nop 0
	s_nop 0
	s_nop 0
	s_nop 0
	s_nop 0
	s_nop 0
	s_nop 0
	s_nop 0
	s_nop 0
	s_nop 0
	s_nop 0
	s_nop 0
	s_nop 0
	s_nop 0
	s_nop 0
	s_nop 0
	s_nop 0
	s_nop 0
	s_nop 0
	s_nop 0
	s_nop 0
	s_nop 0
	s_nop 0
	s_nop 0
	s_nop 0
	s_nop 0
	s_nop 0
	s_nop 0
	s_nop 0
	s_nop 0
	s_nop 0
	s_nop 0
	s_nop 0
	s_nop 0
	s_nop 0
	s_nop 0
	s_nop 0
	s_nop 0
	s_nop 0
	s_nop 0
	s_nop 0
	s_nop 0
	s_nop 0
	s_nop 0
	s_nop 0
	s_nop 0
	s_nop 0
	s_nop 0
	s_nop 0
	s_nop 0
	s_nop 0
	s_nop 0
	s_nop 0
	s_nop 0
	s_nop 0
	s_nop 0
	s_nop 0
	s_nop 0
	s_nop 0
	s_nop 0
	s_nop 0
	s_nop 0
	s_nop 0
	s_nop 0
	s_nop 0
	s_nop 0
	s_nop 0
	s_nop 0
	s_nop 0
	s_nop 0
	s_nop 0
	s_nop 0
	s_nop 0
	s_nop 0
	s_nop 0
	s_nop 0
	s_nop 0
	s_nop 0
	s_nop 0
	s_nop 0
	s_nop 0
	s_nop 0
	s_nop 0
	s_nop 0
	s_nop 0
	s_nop 0
	s_nop 0
	s_nop 0
	s_nop 0
	s_nop 0
	s_nop 0
	s_nop 0
	s_nop 0
	s_nop 0
	s_nop 0
	s_nop 0
	s_nop 0
	s_nop 0
	s_nop 0
	s_nop 0
	s_nop 0
	s_nop 0
	s_nop 0
	s_nop 0
	s_nop 0
	s_nop 0
	s_nop 0
	s_nop 0
	s_nop 0
	s_nop 0
	s_nop 0
	s_nop 0
	s_nop 0
	s_nop 0
	s_nop 0
	s_nop 0
	s_nop 0
	s_nop 0
	s_nop 0
	s_nop 0
	s_nop 0
	s_nop 0
	s_nop 0
	s_nop 0
	s_nop 0
	s_nop 0
	s_nop 0
	s_nop 0
	s_nop 0
	s_nop 0
	s_nop 0
	s_nop 0
	s_nop 0
	s_nop 0
	s_nop 0
	s_nop 0
	s_nop 0
	s_nop 0
	s_nop 0
	s_nop 0
	s_nop 0
	s_nop 0
	s_nop 0
	s_nop 0
	s_nop 0
	s_nop 0
	s_nop 0
	s_nop 0
	s_nop 0
	s_nop 0
	s_nop 0
	s_nop 0
	s_nop 0
	s_nop 0
	s_nop 0
	s_nop 0
	s_nop 0
	s_nop 0
	s_nop 0
	s_nop 0
	s_nop 0
	s_nop 0
	s_nop 0
	s_nop 0
	s_nop 0
	s_nop 0
	s_nop 0
	s_nop 0
	s_nop 0
	s_nop 0
	s_nop 0
	s_nop 0
	s_nop 0
	s_nop 0
	s_nop 0
	s_nop 0
	s_nop 0
	s_nop 0
	s_nop 0
	s_nop 0
	s_nop 0
	s_nop 0
	s_nop 0
	s_nop 0
	s_nop 0
	s_nop 0
	s_nop 0
	s_nop 0
	s_nop 0
	s_nop 0
	s_nop 0
	s_nop 0
	s_nop 0
	s_nop 0
	s_nop 0
	s_nop 0
	s_nop 0
	s_nop 0
	s_nop 0
	s_nop 0
	s_nop 0
	s_nop 0
	s_nop 0
	s_nop 0
	s_nop 0
	s_nop 0
	s_nop 0
	s_nop 0
	s_nop 0
	s_nop 0
	s_nop 0
	s_nop 0
	s_nop 0
	s_nop 0
	s_nop 0
	s_nop 0
	s_nop 0
	s_nop 0
	s_nop 0
	s_nop 0
	s_nop 0
	s_nop 0
	s_nop 0
	s_nop 0
	s_nop 0
	s_nop 0
	s_nop 0
	s_nop 0
	s_nop 0
	s_nop 0
	s_nop 0
	s_nop 0
	s_nop 0
	s_nop 0
	s_nop 0
	s_nop 0
	s_nop 0
	s_nop 0
	s_nop 0
	s_nop 0
	s_nop 0
	s_nop 0
	s_nop 0
	s_nop 0
	s_nop 0
	s_nop 0
	s_nop 0
	s_nop 0
	s_nop 0
	s_nop 0
	s_nop 0
	s_nop 0
	s_nop 0
	s_nop 0
	s_nop 0
	s_nop 0
	s_nop 0
	s_nop 0
	s_nop 0
	s_nop 0
	s_nop 0
	s_nop 0
	s_nop 0
	s_nop 0
	s_nop 0
	s_nop 0
	s_nop 0
	s_nop 0
	s_nop 0
	s_nop 0
	s_nop 0
	s_nop 0
	s_nop 0
	s_nop 0
	s_nop 0
	s_nop 0
	s_nop 0
	s_nop 0
	s_nop 0
	s_nop 0
	s_nop 0
	s_nop 0
	s_nop 0
	s_nop 0
	s_nop 0
	s_nop 0
	s_nop 0
	s_nop 0
	s_nop 0
	s_nop 0
	s_nop 0
	s_nop 0
	s_nop 0
	s_nop 0
	s_nop 0
	s_nop 0
	s_nop 0
	s_nop 0
	s_nop 0
	s_nop 0
	s_nop 0
	s_nop 0
	s_nop 0
	s_nop 0
	s_nop 0
	s_nop 0
	s_nop 0
	s_nop 0
	s_nop 0
	s_nop 0
	s_nop 0
	s_nop 0
	s_nop 0
	s_nop 0
	s_nop 0
	s_nop 0
	s_nop 0
	s_nop 0
	s_nop 0
	s_nop 0
	s_nop 0
	s_nop 0
	s_nop 0
	s_nop 0
	s_nop 0
	s_nop 0
	s_nop 0
	s_nop 0
	s_nop 0
	s_nop 0
	s_nop 0
	s_nop 0
	s_nop 0
	s_nop 0
	s_nop 0
	s_nop 0
	s_nop 0
	s_nop 0
	s_nop 0
	s_nop 0
	s_nop 0
	s_nop 0
	s_nop 0
	s_nop 0
	s_nop 0
	s_nop 0
	s_nop 0
	s_nop 0
	s_nop 0
	s_nop 0
	s_nop 0
	s_nop 0
	s_nop 0
	s_nop 0
	s_nop 0
	s_nop 0
	s_nop 0
	s_nop 0
	s_nop 0
	s_nop 0
	s_nop 0
	s_nop 0
	s_nop 0
	s_nop 0
	s_nop 0
	s_nop 0
	s_nop 0
	s_nop 0
	s_nop 0
	s_nop 0
	s_nop 0
	s_nop 0
	s_nop 0
	s_nop 0
	s_nop 0
	s_nop 0
	s_nop 0
	s_nop 0
	s_nop 0
	s_nop 0
	s_nop 0
	s_nop 0
	s_nop 0
	s_nop 0
	s_nop 0
	s_nop 0
	s_nop 0
	s_nop 0
	s_nop 0
	s_nop 0
	s_nop 0
	s_nop 0
	s_nop 0
	s_nop 0
	s_nop 0
	s_nop 0
	s_nop 0
	s_nop 0
	s_nop 0
	s_nop 0
	s_nop 0
	s_nop 0
	s_nop 0
	s_nop 0
	s_nop 0
	s_nop 0
	s_nop 0
	s_nop 0
	s_nop 0
	s_nop 0
	s_nop 0
	s_nop 0
	s_nop 0
	s_nop 0
	s_nop 0
	s_nop 0
	s_nop 0
	s_nop 0
	s_nop 0
	s_nop 0
	s_nop 0
	s_nop 0
	s_nop 0
	s_nop 0
	s_nop 0
	s_nop 0
	s_nop 0
	s_nop 0
	s_nop 0
	s_nop 0
	s_nop 0
	s_nop 0
	s_nop 0
	s_nop 0
	s_nop 0
	s_nop 0
	s_nop 0
	s_nop 0
	s_nop 0
	s_nop 0
	s_nop 0
	s_nop 0
	s_nop 0
	s_nop 0
	s_nop 0
	s_nop 0
	s_nop 0
	s_nop 0
	s_nop 0
	s_nop 0
	s_nop 0
	s_nop 0
	s_nop 0
	s_nop 0
	s_nop 0
	s_nop 0
	s_nop 0
	s_nop 0
	s_nop 0
	s_nop 0
	s_nop 0
	s_nop 0
	s_nop 0
	s_nop 0
	s_nop 0
	s_nop 0
	s_nop 0
	s_nop 0
	s_nop 0
	s_nop 0
	s_nop 0
	s_nop 0
	s_nop 0
	s_nop 0
	s_nop 0
	s_nop 0
	s_nop 0
	s_nop 0
	s_nop 0
	s_nop 0
	s_nop 0
	s_nop 0
	s_nop 0
	s_nop 0
	s_nop 0
	s_nop 0
	s_nop 0
	s_nop 0
	s_nop 0
	s_nop 0
	s_nop 0
	s_nop 0
	s_nop 0
	s_nop 0
	s_nop 0
	s_nop 0
	s_nop 0
	s_nop 0
	s_nop 0
	s_nop 0
	s_nop 0
	s_nop 0
	s_nop 0
	s_nop 0
	s_nop 0
	s_nop 0
	s_nop 0
	s_nop 0
	s_nop 0
	s_nop 0
	s_nop 0
	s_nop 0
	s_nop 0
	s_nop 0
	s_nop 0
	s_nop 0
	s_nop 0
	s_nop 0
	s_nop 0
	s_nop 0
	s_nop 0
	s_nop 0
	s_nop 0
	s_nop 0
	s_nop 0
	s_nop 0
	s_nop 0
	s_nop 0
	s_nop 0
	s_nop 0
	s_nop 0
	s_nop 0
	s_nop 0
; #define PG8_BAR __builtin_amdgcn_s_barrier()
; template <class Epi, class Sched, bool ALIGN_EPI = false, bool SP2 = false>
; __device__ __forceinline__ void gemm_phase(PG8_LAS unsigned char* lds, int tid_in, const Gemm g, const Sched& S, const Epi& E) {
;     ...
;         if constexpr (ALIGN_EPI) { if (wr == 1) PG8_BAR; }
;     }
	s_nop 0
	s_nop 0
	s_nop 0
	s_nop 0
	s_nop 0
	s_nop 0
	s_nop 0
	s_nop 0
	s_nop 0
	s_nop 0
	s_nop 0
	s_nop 0
	s_nop 0
	s_nop 0
	s_nop 0
	s_nop 0
	s_nop 0
	s_nop 0
	s_nop 0
	s_nop 0
	s_nop 0
	s_nop 0
	s_nop 0
	s_nop 0
	s_nop 0
	s_nop 0
	s_nop 0
	s_nop 0
	s_nop 0
	s_nop 0
	s_nop 0
	s_nop 0
	s_nop 0
	s_nop 0
	s_nop 0
	s_nop 0
	s_nop 0
	s_nop 0
	s_nop 0
	s_nop 0
	s_nop 0
	s_nop 0
	s_nop 0
	s_nop 0
	s_nop 0
	s_nop 0
	s_nop 0
	s_nop 0
	s_nop 0
	s_nop 0
	s_nop 0
	s_nop 0
	s_nop 0
	s_nop 0
	s_nop 0
	s_nop 0
	s_nop 0
	s_nop 0
	s_nop 0
	s_nop 0
	s_nop 0
	s_nop 0
	s_nop 0
	s_nop 0
	s_nop 0
	s_nop 0
	s_nop 0
	s_nop 0
	s_nop 0
	s_nop 0
	s_nop 0
	s_nop 0
	s_nop 0
	s_nop 0
	s_nop 0
	s_nop 0
	s_nop 0
	s_nop 0
	s_nop 0
	s_nop 0
	s_nop 0
	s_nop 0
	s_nop 0
	s_nop 0
	s_nop 0
	s_nop 0
	s_nop 0
	s_nop 0
	s_nop 0
	s_nop 0
	s_nop 0
	s_nop 0
	s_nop 0
	s_nop 0
	s_nop 0
	s_nop 0
	s_nop 0
	s_nop 0
	s_nop 0
	s_nop 0
	s_nop 0
	s_nop 0
	s_nop 0
	s_nop 0
	s_nop 0
	s_nop 0
	s_nop 0
	s_nop 0
	s_nop 0
	s_nop 0
	s_nop 0
	s_nop 0
	s_nop 0
	s_nop 0
	s_nop 0
	s_nop 0
	s_nop 0
	s_nop 0
	s_nop 0
	s_nop 0
	s_nop 0
	s_nop 0
	s_nop 0
	s_nop 0
	s_nop 0
	s_nop 0
	s_nop 0
	s_nop 0
	s_nop 0
	s_nop 0
	s_nop 0
	s_nop 0
	s_nop 0
	s_nop 0
	s_nop 0
	s_nop 0
	s_nop 0
	s_nop 0
	s_nop 0
	s_nop 0
	s_nop 0
	s_nop 0
	s_nop 0
	s_nop 0
	s_nop 0
	s_nop 0
	s_nop 0
	s_nop 0
	s_nop 0
	s_nop 0
	s_nop 0
	s_nop 0
	s_nop 0
	s_nop 0
	s_nop 0
	s_nop 0
	s_nop 0
	s_nop 0
	s_nop 0
	s_nop 0
	s_nop 0
	s_nop 0
	s_nop 0
	s_nop 0
	s_nop 0
	s_nop 0
	s_nop 0
	s_nop 0
	s_nop 0
	s_nop 0
	s_nop 0
	s_nop 0
	s_nop 0
	s_nop 0
	s_nop 0
	s_nop 0
	s_nop 0
	s_nop 0
	s_nop 0
	s_nop 0
	s_nop 0
	s_nop 0
	s_nop 0
	s_nop 0
	s_nop 0
	s_nop 0
	s_nop 0
	s_nop 0
	s_nop 0
	s_nop 0
	s_nop 0
	s_nop 0
	s_nop 0
	s_nop 0
	s_nop 0
	s_nop 0
	s_nop 0
	s_nop 0
	s_nop 0
	s_nop 0
	s_nop 0
	s_nop 0
	s_nop 0
	s_nop 0
	s_nop 0
	s_nop 0
	s_nop 0
	s_nop 0
	s_nop 0
	s_nop 0
	s_nop 0
	s_nop 0
	s_nop 0
	s_nop 0
	s_nop 0
	s_nop 0
	s_nop 0
	s_nop 0
	s_nop 0
	s_nop 0
	s_nop 0
	s_nop 0
	s_nop 0
	s_nop 0
	s_nop 0
	s_nop 0
	s_nop 0
	s_nop 0
	s_nop 0
	s_nop 0
	s_nop 0
	s_nop 0
	s_nop 0
	s_nop 0
	s_nop 0
	s_nop 0
	s_nop 0
	s_nop 0
	s_nop 0
	s_nop 0
	s_nop 0
	s_nop 0
	s_nop 0
	s_nop 0
	s_nop 0
	s_nop 0
	s_nop 0
	s_nop 0
	s_nop 0
	s_nop 0
	s_nop 0
	s_nop 0
	s_nop 0
	s_nop 0
	s_nop 0
	s_nop 0
	s_nop 0
	s_nop 0
	s_nop 0
	s_nop 0
	s_nop 0
	s_nop 0
	s_nop 0
	s_nop 0
	s_nop 0
	s_nop 0
	s_nop 0
	s_nop 0
	s_nop 0
	s_nop 0
	s_nop 0
	s_nop 0
	s_nop 0
	s_nop 0
	s_nop 0
	s_nop 0
	s_nop 0
	s_nop 0
	s_nop 0
	s_nop 0
	s_nop 0
	s_nop 0
	s_nop 0
	s_nop 0
	s_nop 0
	s_nop 0
	s_nop 0
	s_nop 0
	s_nop 0
	s_nop 0
	s_nop 0
	s_nop 0
	s_nop 0
	s_nop 0
	s_nop 0
	s_nop 0
	s_nop 0
	s_nop 0
	s_nop 0
	s_nop 0
	s_nop 0
	s_nop 0
	s_nop 0
	s_nop 0
	s_nop 0
	s_nop 0
	s_nop 0
	s_nop 0
	s_nop 0
	s_nop 0
	s_nop 0
	s_nop 0
	s_nop 0
	s_nop 0
	s_nop 0
	s_nop 0
	s_nop 0
	s_nop 0
	s_nop 0
	s_nop 0
	s_nop 0
	s_nop 0
	s_nop 0
	s_nop 0
	s_nop 0
	s_nop 0
	s_nop 0
	s_nop 0
	s_nop 0
	s_nop 0
	s_nop 0
	s_nop 0
	s_nop 0
	s_nop 0
	s_nop 0
	s_nop 0
	s_nop 0
	s_nop 0
	s_nop 0
	s_nop 0
	s_nop 0
	s_nop 0
	s_nop 0
	s_nop 0
	s_nop 0
	s_nop 0
	s_nop 0
	s_nop 0
	s_nop 0
	s_nop 0
	s_nop 0
	s_nop 0
	s_nop 0
	s_nop 0
	s_nop 0
	s_nop 0
	s_nop 0
	s_nop 0
	s_nop 0
	s_nop 0
	s_nop 0
	s_nop 0
	s_nop 0
	s_nop 0
	s_nop 0
	s_nop 0
	s_nop 0
	s_nop 0
	s_nop 0
	s_nop 0
	s_nop 0
	s_nop 0
	s_nop 0
	s_nop 0
	s_nop 0
	s_nop 0
	s_nop 0
	s_nop 0
	s_nop 0
	s_nop 0
	s_nop 0
	s_nop 0
	s_nop 0
	s_nop 0
	s_nop 0
	s_nop 0
	s_nop 0
	s_nop 0
	s_nop 0
	s_nop 0
	s_nop 0
	s_nop 0
	s_nop 0
	s_nop 0
	s_nop 0
	s_nop 0
	s_nop 0
	s_nop 0
	s_nop 0
	s_nop 0
	s_nop 0
	s_nop 0
	s_nop 0
	s_nop 0
	s_nop 0
	s_nop 0
	s_nop 0
	s_nop 0
	s_nop 0
	s_nop 0
	s_nop 0
	s_nop 0
	s_nop 0
	s_nop 0
	s_nop 0
	s_nop 0
	s_nop 0
	s_nop 0
	s_nop 0
	s_nop 0
	s_nop 0
	s_nop 0
	s_nop 0
	s_nop 0
	s_nop 0
	s_nop 0
	s_nop 0
	s_nop 0
	s_nop 0
	s_nop 0
	s_nop 0
	s_nop 0
	s_nop 0
	s_nop 0
	s_nop 0
	s_nop 0
	s_nop 0
	s_nop 0
	s_nop 0
	s_nop 0
	s_nop 0
	s_nop 0
	s_nop 0
	s_nop 0
	s_nop 0
	s_nop 0
	s_nop 0
	s_nop 0
	s_nop 0
	s_nop 0
	s_nop 0
	s_nop 0
	s_nop 0
	s_nop 0
	s_nop 0
	s_nop 0
	s_nop 0
	s_nop 0
	s_nop 0
	s_nop 0
	s_nop 0
	s_nop 0
	s_nop 0
	s_nop 0
	s_nop 0
	s_nop 0
	s_nop 0
	s_nop 0
	s_nop 0
	s_nop 0
	s_nop 0
	s_nop 0
	s_nop 0
	s_nop 0
	s_nop 0
	s_nop 0
	s_nop 0
	s_nop 0
	s_nop 0
	s_nop 0
	s_nop 0
	s_nop 0
	s_nop 0
	s_nop 0
	s_nop 0
	s_nop 0
	s_nop 0
	s_nop 0
	s_nop 0
	s_nop 0
	s_nop 0
	s_nop 0
	s_nop 0
	s_nop 0
	s_nop 0
	s_nop 0
	s_nop 0
	s_nop 0
	s_nop 0
	s_nop 0
	s_nop 0
	s_nop 0
	s_nop 0
	s_nop 0
	s_nop 0
	s_nop 0
	s_nop 0
	s_nop 0
	s_nop 0
	s_nop 0
	s_nop 0
	s_nop 0
	s_nop 0
	s_nop 0
	s_nop 0
	s_nop 0
	s_nop 0
	s_nop 0
	s_nop 0
	s_nop 0
	s_nop 0
	s_nop 0
	s_nop 0
	s_nop 0
	s_nop 0
	s_nop 0
	s_nop 0
	s_nop 0
	s_nop 0
	s_nop 0
	s_nop 0
	s_nop 0
	s_nop 0
	s_nop 0
	s_nop 0
	s_nop 0
	s_nop 0
	s_nop 0
	s_nop 0
	s_nop 0
	s_nop 0
	s_nop 0
	s_nop 0
	s_nop 0
	s_nop 0
	s_nop 0
	s_nop 0
	s_nop 0
	s_nop 0
	s_nop 0
	s_nop 0
	s_nop 0
	s_nop 0
	s_nop 0
	s_nop 0
	s_nop 0
	s_nop 0
	s_nop 0
	s_nop 0
	s_nop 0
	s_nop 0
	s_nop 0
	s_nop 0
	s_nop 0
	s_nop 0
	s_nop 0
	s_nop 0
	s_nop 0
	s_nop 0
	s_nop 0
	s_nop 0
	s_nop 0
	s_nop 0
	s_nop 0
	s_nop 0
	s_nop 0
	s_nop 0
	s_nop 0
	s_nop 0
	s_nop 0
	s_nop 0
	s_nop 0
	s_nop 0
	s_nop 0
	s_nop 0
	s_nop 0
	s_nop 0
	s_nop 0
	s_nop 0
	s_nop 0
	s_nop 0
	s_nop 0
	s_nop 0
	s_nop 0
	s_nop 0
	s_nop 0
	s_nop 0
	s_nop 0
	s_nop 0
	s_nop 0
	s_nop 0
	s_nop 0
	s_nop 0
	s_nop 0
	s_nop 0
	s_nop 0
	s_nop 0
	s_nop 0
	s_nop 0
	s_nop 0
	s_nop 0
	s_nop 0
	s_nop 0
	s_nop 0
	s_nop 0
	s_nop 0
	s_nop 0
	s_nop 0
	s_nop 0
	s_nop 0
	s_nop 0
	s_nop 0
	s_nop 0
	s_nop 0
	s_nop 0
	s_nop 0
	s_nop 0
; #define PG8_BAR __builtin_amdgcn_s_barrier()
; template <class Epi, class Sched, bool ALIGN_EPI = false, bool SP2 = false>
; __device__ __forceinline__ void gemm_phase(PG8_LAS unsigned char* lds, int tid_in, const Gemm g, const Sched& S, const Epi& E) {
;     ...
;         if constexpr (ALIGN_EPI) { if (wr == 1) PG8_BAR; }
;     }
	s_nop 0
	s_nop 0
	s_nop 0
	s_nop 0
	s_nop 0
	s_nop 0
	s_nop 0
	s_nop 0
	s_nop 0
	s_nop 0
	s_nop 0
	s_nop 0
	s_nop 0
	s_nop 0
	s_nop 0
	s_nop 0
	s_nop 0
	s_nop 0
	s_nop 0
	s_nop 0
	s_nop 0
	s_nop 0
	s_nop 0
	s_nop 0
	s_nop 0
	s_nop 0
	s_nop 0
	s_nop 0
	s_nop 0
	s_nop 0
	s_nop 0
	s_nop 0
	s_nop 0
	s_nop 0
	s_nop 0
	s_nop 0
	s_nop 0
	s_nop 0
	s_nop 0
	s_nop 0
	s_nop 0
	s_nop 0
	s_nop 0
	s_nop 0
	s_nop 0
	s_nop 0
	s_nop 0
	s_nop 0
	s_nop 0
	s_nop 0
	s_nop 0
	s_nop 0
	s_nop 0
	s_nop 0
	s_nop 0
	s_nop 0
	s_nop 0
	s_nop 0
	s_nop 0
	s_nop 0
	s_nop 0
	s_nop 0
	s_nop 0
	s_nop 0
	s_nop 0
	s_nop 0
	s_nop 0
	s_nop 0
	s_nop 0
	s_nop 0
	s_nop 0
	s_nop 0
	s_nop 0
	s_nop 0
	s_nop 0
	s_nop 0
	s_nop 0
	s_nop 0
	s_nop 0
	s_nop 0
	s_nop 0
	s_nop 0
	s_nop 0
	s_nop 0
	s_nop 0
	s_nop 0
	s_nop 0
	s_nop 0
	s_nop 0
	s_nop 0
	s_nop 0
	s_nop 0
	s_nop 0
	s_nop 0
	s_nop 0
	s_nop 0
	s_nop 0
	s_nop 0
	s_nop 0
	s_nop 0
	s_nop 0
	s_nop 0
	s_nop 0
	s_nop 0
	s_nop 0
	s_nop 0
	s_nop 0
	s_nop 0
	s_nop 0
	s_nop 0
	s_nop 0
	s_nop 0
	s_nop 0
	s_nop 0
	s_nop 0
	s_nop 0
	s_nop 0
	s_nop 0
	s_nop 0
	s_nop 0
	s_nop 0
	s_nop 0
	s_nop 0
	s_nop 0
	s_nop 0
	s_nop 0
	s_nop 0
	s_nop 0
	s_nop 0
	s_nop 0
	s_nop 0
	s_nop 0
	s_nop 0
	s_nop 0
	s_nop 0
	s_nop 0
	s_nop 0
	s_nop 0
	s_nop 0
	s_nop 0
	s_nop 0
	s_nop 0
	s_nop 0
	s_nop 0
	s_nop 0
	s_nop 0
	s_nop 0
	s_nop 0
	s_nop 0
	s_nop 0
	s_nop 0
	s_nop 0
	s_nop 0
	s_nop 0
	s_nop 0
	s_nop 0
	s_nop 0
	s_nop 0
	s_nop 0
	s_nop 0
	s_nop 0
	s_nop 0
	s_nop 0
	s_nop 0
	s_nop 0
	s_nop 0
	s_nop 0
	s_nop 0
	s_nop 0
	s_nop 0
	s_nop 0
	s_nop 0
	s_nop 0
	s_nop 0
	s_nop 0
	s_nop 0
	s_nop 0
	s_nop 0
	s_nop 0
	s_nop 0
	s_nop 0
	s_nop 0
	s_nop 0
	s_nop 0
	s_nop 0
	s_nop 0
	s_nop 0
	s_nop 0
	s_nop 0
	s_nop 0
	s_nop 0
	s_nop 0
	s_nop 0
	s_nop 0
	s_nop 0
	s_nop 0
	s_nop 0
	s_nop 0
	s_nop 0
	s_nop 0
	s_nop 0
	s_nop 0
	s_nop 0
	s_nop 0
	s_nop 0
	s_nop 0
	s_nop 0
	s_nop 0
	s_nop 0
	s_nop 0
	s_nop 0
	s_nop 0
	s_nop 0
	s_nop 0
	s_nop 0
	s_nop 0
	s_nop 0
	s_nop 0
	s_nop 0
	s_nop 0
	s_nop 0
	s_nop 0
	s_nop 0
	s_nop 0
	s_nop 0
	s_nop 0
	s_nop 0
	s_nop 0
	s_nop 0
	s_nop 0
	s_nop 0
	s_nop 0
	s_nop 0
	s_nop 0
	s_nop 0
	s_nop 0
	s_nop 0
	s_nop 0
	s_nop 0
	s_nop 0
	s_nop 0
	s_nop 0
	s_nop 0
	s_nop 0
	s_nop 0
	s_nop 0
	s_nop 0
	s_nop 0
	s_nop 0
	s_nop 0
	s_nop 0
	s_nop 0
	s_nop 0
	s_nop 0
	s_nop 0
	s_nop 0
	s_nop 0
	s_nop 0
	s_nop 0
	s_nop 0
	s_nop 0
	s_nop 0
	s_nop 0
	s_nop 0
	s_nop 0
	s_nop 0
	s_nop 0
	s_nop 0
	s_nop 0
	s_nop 0
	s_nop 0
	s_nop 0
	s_nop 0
	s_nop 0
	s_nop 0
	s_nop 0
	s_nop 0
	s_nop 0
	s_nop 0
	s_nop 0
	s_nop 0
	s_nop 0
	s_nop 0
	s_nop 0
	s_nop 0
	s_nop 0
	s_nop 0
	s_nop 0
	s_nop 0
	s_nop 0
	s_nop 0
	s_nop 0
	s_nop 0
	s_nop 0
	s_nop 0
	s_nop 0
	s_nop 0
	s_nop 0
	s_nop 0
	s_nop 0
	s_nop 0
	s_nop 0
	s_nop 0
	s_nop 0
	s_nop 0
	s_nop 0
	s_nop 0
	s_nop 0
	s_nop 0
	s_nop 0
	s_nop 0
	s_nop 0
	s_nop 0
	s_nop 0
	s_nop 0
	s_nop 0
	s_nop 0
	s_nop 0
	s_nop 0
	s_nop 0
	s_nop 0
	s_nop 0
	s_nop 0
	s_nop 0
	s_nop 0
	s_nop 0
	s_nop 0
	s_nop 0
	s_nop 0
	s_nop 0
	s_nop 0
	s_nop 0
	s_nop 0
	s_nop 0
	s_nop 0
	s_nop 0
	s_nop 0
	s_nop 0
	s_nop 0
	s_nop 0
	s_nop 0
	s_nop 0
	s_nop 0
	s_nop 0
	s_nop 0
	s_nop 0
	s_nop 0
	s_nop 0
	s_nop 0
	s_nop 0
	s_nop 0
	s_nop 0
	s_nop 0
	s_nop 0
	s_nop 0
	s_nop 0
	s_nop 0
	s_nop 0
	s_nop 0
	s_nop 0
	s_nop 0
	s_nop 0
	s_nop 0
	s_nop 0
	s_nop 0
	s_nop 0
	s_nop 0
	s_nop 0
	s_nop 0
	s_nop 0
	s_nop 0
	s_nop 0
	s_nop 0
	s_nop 0
	s_nop 0
	s_nop 0
	s_nop 0
	s_nop 0
	s_nop 0
	s_nop 0
	s_nop 0
	s_nop 0
	s_nop 0
	s_nop 0
	s_nop 0
	s_nop 0
	s_nop 0
	s_nop 0
	s_nop 0
	s_nop 0
	s_nop 0
	s_nop 0
	s_nop 0
	s_nop 0
	s_nop 0
	s_nop 0
	s_nop 0
	s_nop 0
	s_nop 0
	s_nop 0
	s_nop 0
	s_nop 0
	s_nop 0
	s_nop 0
	s_nop 0
	s_nop 0
	s_nop 0
	s_nop 0
	s_nop 0
	s_nop 0
	s_nop 0
	s_nop 0
	s_nop 0
	s_nop 0
	s_nop 0
	s_nop 0
	s_nop 0
	s_nop 0
	s_nop 0
	s_nop 0
	s_nop 0
	s_nop 0
	s_nop 0
	s_nop 0
	s_nop 0
	s_nop 0
	s_nop 0
	s_nop 0
	s_nop 0
	s_nop 0
	s_nop 0
	s_nop 0
	s_nop 0
	s_nop 0
	s_nop 0
	s_nop 0
	s_nop 0
	s_nop 0
	s_nop 0
	s_nop 0
	s_nop 0
	s_nop 0
	s_nop 0
	s_nop 0
	s_nop 0
	s_nop 0
	s_nop 0
	s_nop 0
	s_nop 0
	s_nop 0
	s_nop 0
	s_nop 0
	s_nop 0
	s_nop 0
	s_nop 0
	s_nop 0
	s_nop 0
	s_nop 0
	s_nop 0
	s_nop 0
	s_nop 0
	s_nop 0
	s_nop 0
	s_nop 0
	s_nop 0
	s_nop 0
	s_nop 0
	s_nop 0
	s_nop 0
	s_nop 0
	s_nop 0
	s_nop 0
	s_nop 0
	s_nop 0
	s_nop 0
	s_nop 0
	s_nop 0
	s_nop 0
	s_nop 0
	s_nop 0
	s_nop 0
	s_nop 0
	s_nop 0
	s_nop 0
	s_nop 0
	s_nop 0
	s_nop 0
	s_nop 0
	s_nop 0
	s_nop 0
	s_nop 0
	s_nop 0
	s_nop 0
	s_nop 0
	s_nop 0
	s_nop 0
	s_nop 0
	s_nop 0
	s_nop 0
	s_nop 0
	s_nop 0
	s_nop 0
	s_nop 0
	s_nop 0
	s_nop 0
	s_nop 0
	s_nop 0
	s_nop 0
	s_nop 0
	s_nop 0
	s_nop 0
	s_nop 0
	s_nop 0
	s_nop 0
	s_nop 0
	s_nop 0
	s_nop 0
	s_nop 0
	s_nop 0
	s_nop 0
	s_nop 0
	s_nop 0
	s_nop 0
	s_nop 0
	s_nop 0
	s_nop 0
	s_nop 0
	s_nop 0
	s_nop 0
	s_nop 0
	s_nop 0
	s_nop 0
	s_nop 0
	s_nop 0
	s_nop 0
	s_nop 0
	s_nop 0
	s_nop 0
	s_nop 0
	s_nop 0
	s_nop 0
	s_nop 0
	s_nop 0
	s_nop 0
	s_nop 0
	s_nop 0
	s_nop 0
	s_nop 0
	s_nop 0
	s_nop 0
	s_nop 0
	s_nop 0
	s_nop 0
	s_nop 0
	s_nop 0
	s_nop 0
	s_nop 0
	s_nop 0
	s_nop 0
	s_nop 0
	s_nop 0
	s_nop 0
	s_nop 0
	s_nop 0
	s_nop 0
	s_nop 0
	s_nop 0
	s_nop 0
	s_nop 0
	s_nop 0
	s_nop 0
	s_nop 0
	s_nop 0
	s_nop 0
	s_nop 0
	s_nop 0
	s_nop 0
	s_nop 0
	s_nop 0
	s_nop 0
	s_nop 0
	s_nop 0
	s_nop 0
	s_nop 0
	s_nop 0
	s_nop 0
	s_nop 0
	s_nop 0
	s_nop 0
	s_nop 0
	s_nop 0
	s_nop 0
	s_nop 0
	s_nop 0
	s_nop 0
	s_nop 0
	s_nop 0
	s_nop 0
	s_nop 0
	s_nop 0
	s_nop 0
	s_nop 0
	s_nop 0
	s_nop 0
	s_nop 0
	s_nop 0
	s_nop 0
	s_nop 0
	s_nop 0
	s_nop 0
	s_nop 0
	s_nop 0
	s_nop 0
	s_nop 0
	s_nop 0
	s_nop 0
	s_nop 0
	s_nop 0
	s_nop 0
	s_nop 0
	s_nop 0
	s_nop 0
	s_nop 0
	s_nop 0
	s_nop 0
	s_nop 0
	s_nop 0
	s_nop 0
	s_nop 0
	s_nop 0
	s_nop 0
	s_nop 0
	s_nop 0
	s_nop 0
	s_nop 0
	s_nop 0
	s_nop 0
	s_nop 0
	s_nop 0
	s_nop 0
	s_nop 0
	s_nop 0
	s_nop 0
	s_nop 0
	s_nop 0
	s_nop 0
	s_nop 0
	s_nop 0
	s_nop 0
	s_nop 0
	s_nop 0
	s_nop 0
	s_nop 0
	s_nop 0
	s_nop 0
	s_nop 0
	s_nop 0
	s_nop 0
	s_nop 0
	s_nop 0
	s_nop 0
	s_nop 0
	s_nop 0
	s_nop 0
	s_nop 0
	s_nop 0
	s_nop 0
	s_nop 0
	s_nop 0
	s_nop 0
	s_nop 0
	s_nop 0
	s_nop 0
	s_nop 0
	s_nop 0
	s_nop 0
	s_nop 0
	s_nop 0
	s_nop 0
	s_nop 0
	s_nop 0
	s_nop 0
.LBB0_622:
	s_branch .LBB0_369
